# MLP2F K-loop walks K rotated by 8 K-steps per XCD (channel spread for the 8 KB-stride hid rows)
# baseline (speedup 1.0000x reference)
;     ...
;   const int tid = opaque_tid(), wid = __builtin_amdgcn_readfirstlane(tid >> 6), lane = tid & 63, wr = wid >> 2, wc = wid & 3;
;   constexpr int nt = K / BK;
;   unsigned voff[2], voffB[2];
; #pragma unroll
;   for (int i = 0; i < 2; ++i) {
;     int r_, c_;
;     stage_rc(tid * 16 + i * 8192, r_, c_);
;     voff[i] = (unsigned)(r_ * K + c_) * 2u;
;     const int rho = r_ & 31, nn = rho >> 4, ii = rho & 15;
;     const int rb = (r_ & ~31) + 8 * (ii >> 2) + 4 * nn + (ii & 3);
;     voffB[i] = (unsigned)(rb * K + c_) * 2u;
;   }
;   const size_t kstep = (size_t)(BK * 2);
;   const size_t hstep = (size_t)HALF * K * 2;
;   const size_t tstep = 2 * hstep;
;   const unsigned ldsw = (unsigned)wid * 1024u;
;   const int aoff = lds_byte(wr * 64 + (lane & 15), (lane >> 4) * 8), boff = lds_byte(wc * 32 + (lane & 15), (lane >> 4) * 8);
;   auto unit = [&](int i, int& pm, int& pn, int& kq) -> bool {
;     const long L = (long)i * gridDim.x + blockIdx.x;
;     kq = -1;
;     if (SPLIT && L >= nwg) {
;       const int u = (int)(L - nwg);
;       if (u >= 16 * nMsplit) return false;
;       pm = nM + (u >> 4); pn = (u >> 2) & 3; kq = u & 3;
;       return true;
;     }
;     if (L >= nwg) return false;
;     int wgid = (int)L;
;     {
;       const int q = nwg / NXCD, r = nwg % NXCD, xcd = wgid % NXCD, off = wgid / NXCD;
;       wgid = (xcd < r ? xcd * (q + 1) : r * (q + 1) + (xcd - r) * q) + off;
;     }
;     const int nig = WGM * nN, gid = wgid / nig, fm = gid * WGM, gsz = min(nM - fm, WGM);
;     pm = fm + ((wgid % nig) % gsz);
;     pn = (wgid % nig) / gsz;
;     return true;
;   };
;   int pm, pn, kq, npm = 0, npn = 0, nkq = -1, ui = 0;
;   if (!unit(0, pm, pn, kq)) return;
;   const char* cA = (const char*)A + (size_t)pm * tstep + (kq > 0 ? (size_t)kq * (K / 4) * 2 : 0);
;   const char* cB = (const char*)Bt + (size_t)pn * tstep + (kq > 0 ? (size_t)kq * (K / 4) * 2 : 0);
;   f32x4 acc[2][2][4][2];
; #pragma unroll
;   for (int a = 0; a < 2; ++a)
; #pragma unroll
;     for (int b = 0; b < 2; ++b)
; #pragma unroll
;       for (int m = 0; m < 4; ++m)
; #pragma unroll
;         for (int n = 0; n < 2; ++n) acc[a][b][m][n] = (f32x4){0.f, 0.f, 0.f, 0.f};
;   bf16x8 At[4][2], B0[2][2], B1[2][2];
;   STAGE(SBo(0, 0), cB, voffB); STAGE(SBo(0, 1), cB + hstep, voffB); STAGE(SAo(0, 0), cA, voff); STAGE(SAo(0, 1), cA + hstep, voff);
;   if (wr == 1) BAR;
;   WAIT_V(2); BAR;
.LBB0_1131:
	v_readlane_b32 s0, v255, 13
	v_readlane_b32 s1, v255, 14
	s_and_b64 vcc, exec, s[0:1]
	s_mov_b64 s[0:1], 0
	s_cbranch_vccnz .LBB0_1180
	s_and_b32 s100, s57, 7
	s_lshl_b32 s101, s100, 3
	s_sub_i32 s101, 60, s101
	s_cmp_eq_u32 s100, 0
	s_cselect_b32 s101, 0x7fffffff, s101
	s_lshl_b32 s100, s100, 10
	v_ashrrev_i32_e32 v0, 31, v16
	v_lshrrev_b32_e32 v0, 26, v0
	v_add_u32_e32 v0, v16, v0
	v_ashrrev_i32_e32 v10, 6, v0
	v_bfe_i32 v0, v16, 27, 1
	s_waitcnt vmcnt(11)
	v_lshlrev_b32_e32 v2, 4, v16
	v_lshrrev_b32_e32 v0, 22, v0
	v_add_u32_e32 v0, v2, v0
	v_and_b32_e32 v0, 0xfffffc00, v0
	v_sub_u32_e32 v0, v2, v0
	v_lshrrev_b32_e32 v3, 4, v0
	v_bitop3_b32 v3, v3, v0, 32 bitop3:0x6c
	v_ashrrev_i32_e32 v0, 31, v0
	v_lshrrev_b32_e32 v0, 26, v0
	v_add_u32_e32 v0, v3, v0
	v_ashrrev_i32_e32 v11, 6, v0
	v_lshlrev_b32_e32 v4, 3, v10
	v_mul_i32_i24_e32 v5, 64, v11
	v_and_b32_e32 v4, -16, v4
	v_sub_u32_e32 v3, v3, v5
	v_add_u32_e32 v0, v11, v4
	v_lshlrev_b32_e32 v4, 5, v10
	v_ashrrev_i16_sdwa v3, v237, sext(v3) dst_sel:DWORD dst_unused:UNUSED_PAD src0_sel:DWORD src1_sel:BYTE_0
	v_and_b32_e32 v4, 32, v4
	v_bfe_i32 v12, v3, 0, 16
	v_add_lshl_u32 v3, v4, v12, 1
	v_lshlrev_b32_e32 v4, 1, v0
	v_lshrrev_b32_e32 v5, 2, v0
	s_waitcnt vmcnt(10)
	v_and_b32_e32 v6, 3, v11
	s_mov_b32 s1, 0x7ffe0
	v_lshl_add_u32 v162, v0, 13, v3
	v_and_b32_e32 v4, 24, v4
	v_and_b32_e32 v5, 4, v5
	v_and_or_b32 v0, v0, s1, v6
	v_or3_b32 v0, v0, v4, v5
	v_add_u32_e32 v2, 0x2000, v2
	v_lshl_add_u32 v0, v0, 13, v3
	v_ashrrev_i32_e32 v3, 31, v2
	v_lshrrev_b32_e32 v3, 22, v3
	v_add_u32_e32 v3, v2, v3
	v_ashrrev_i32_e32 v13, 10, v3
	v_mul_i32_i24_e32 v3, 0x400, v13
	v_sub_u32_e32 v2, v2, v3
	v_lshrrev_b32_e32 v3, 4, v2
	v_bitop3_b32 v2, v3, v2, 32 bitop3:0x6c
	v_ashrrev_i32_e32 v4, 31, v2
	v_lshrrev_b32_e32 v4, 26, v4
	v_add_u32_e32 v4, v2, v4
	v_ashrrev_i32_e32 v14, 6, v4
	v_and_b32_e32 v4, 0xc0, v4
	v_sub_u32_e32 v2, v2, v4
	v_lshlrev_b32_e32 v3, 3, v13
	v_lshlrev_b32_e32 v5, 5, v13
	v_ashrrev_i16_sdwa v2, v237, sext(v2) dst_sel:DWORD dst_unused:UNUSED_PAD src0_sel:DWORD src1_sel:BYTE_0
	v_and_b32_e32 v3, -16, v3
	v_and_b32_e32 v5, 32, v5
	v_bfe_i32 v15, v2, 0, 16
	s_ashr_i32 s0, s7, 6
	v_add_u32_e32 v3, v14, v3
	v_add_lshl_u32 v2, v5, v15, 1
	v_and_b32_e32 v6, 3, v14
	s_ashr_i32 s15, s14, 31
	s_ashr_i32 s17, s16, 31
	v_lshl_add_u32 v164, v3, 13, v2
	v_lshlrev_b32_e32 v4, 1, v3
	v_lshrrev_b32_e32 v5, 2, v3
	v_and_or_b32 v3, v3, s1, v6
	s_ashr_i32 s1, s7, 8
	s_lshl_b32 s26, s0, 10
	s_lshl_b64 s[4:5], s[14:15], 21
	s_lshl_b64 s[8:9], s[16:17], 21
	s_add_u32 s20, s24, s8
	s_addc_u32 s21, s25, s9
	s_add_u32 s20, s20, s100
	s_addc_u32 s21, s21, 0
	s_add_i32 s27, s26, 0
	v_and_b32_e32 v4, 24, v4
	v_and_b32_e32 v5, 4, v5
	s_add_i32 m0, s27, 0x10000
	v_or3_b32 v3, v3, v4, v5
	global_load_lds_dwordx4 v0, s[20:21]
	s_add_i32 m0, s27, 0x12000
	v_lshl_add_u32 v166, v3, 13, v2
	s_add_u32 s8, s20, 0x100000
	global_load_lds_dwordx4 v166, s[20:21]
	s_addc_u32 s9, s21, 0
	s_add_i32 m0, s27, 0x14000
	v_mov_b32_e32 v167, v1
	global_load_lds_dwordx4 v0, s[8:9]
	s_add_i32 m0, s27, 0x16000
	s_add_u32 s18, s84, s4
	s_addc_u32 s19, s85, s5
	s_add_u32 s18, s18, s100
	s_addc_u32 s19, s19, 0
	s_add_i32 s29, s27, 0x2000
	global_load_lds_dwordx4 v166, s[8:9]
	s_mov_b32 m0, s27
	s_add_u32 s4, s18, 0x100000
	global_load_lds_dwordx4 v162, s[18:19]
	s_mov_b32 m0, s29
	s_addc_u32 s5, s19, 0
	s_add_i32 s30, s27, 0x4000
	global_load_lds_dwordx4 v164, s[18:19]
	s_mov_b32 m0, s30
	s_add_i32 s31, s27, 0x6000
	global_load_lds_dwordx4 v162, s[4:5]
	s_mov_b32 m0, s31
	v_mov_b32_e32 v163, v1
	global_load_lds_dwordx4 v164, s[4:5]
	v_mov_b32_e32 v165, v1
	s_cmp_eq_u32 s1, 1
	v_lshl_add_u64 v[8:9], s[20:21], 0, v[0:1]
	v_lshl_add_u64 v[6:7], s[20:21], 0, v[166:167]
	v_lshl_add_u64 v[2:3], s[18:19], 0, v[162:163]
	s_cselect_b64 s[4:5], -1, 0
	s_cmp_lg_u32 s1, 1
	v_lshl_add_u64 v[4:5], s[18:19], 0, v[164:165]
	s_cbranch_scc1 .LBB0_1134
	s_barrier

; #define SCHED __builtin_amdgcn_sched_barrier(0)
;     ...
;     const bool has_next = unit(ui + 1, npm, npn, nkq);
;     const char* nA = has_next ? (const char*)A + (size_t)npm * tstep + (nkq > 0 ? (size_t)nkq * (K / 4) * 2 : 0) : cA;
;     const char* nB = has_next ? (const char*)Bt + (size_t)npn * tstep + (nkq > 0 ? (size_t)nkq * (K / 4) * 2 : 0) : cB;
;     const int ntu = (SPLIT && kq >= 0) ? nt / 4 : nt;
;     for (int t = 0; t < ntu; t += 2) {
;       const bool last = (t == ntu - 2);
;       const char* a1 = cA + (size_t)(t + 1) * kstep;
;       const char* a2 = last ? nA : cA + (size_t)(t + 2) * kstep;
;       const char* b2 = last ? nB : cB + (size_t)(t + 2) * kstep;
;       const char* a3 = a2 + kstep;
;       const char* b3 = b2 + kstep;
;       LDB(B0, 0, 0); LDB(B1, 0, 1); SCHED; LDA(At, 0, 0); STAGE(SAo(1, 1), a1 + hstep, voff);
;     ...
; #pragma unroll
;     for (int a = 0; a < 2; ++a)
; #pragma unroll
;       for (int b = 0; b < 2; ++b)
; #pragma unroll
;         for (int m = 0; m < 4; ++m)
; #pragma unroll
;           for (int n = 0; n < 2; ++n) acc[a][b][m][n] = (f32x4){0.f, 0.f, 0.f, 0.f};
;     pm = npm; pn = npn; kq = nkq; cA = nA; cB = nB; ++ui;
.LBB0_1139:
	s_nop 0
	v_readlane_b32 s10, v254, 34
	v_readlane_b32 s11, v254, 35
	s_lshl_b64 s[10:11], s[10:11], 21
	s_add_u32 s10, s84, s10
	s_addc_u32 s11, s85, s11
	s_add_u32 s10, s10, s100
	s_addc_u32 s11, s11, 0
	s_and_b64 s[12:13], s[0:1], exec
	s_cselect_b32 s15, s11, s19
	s_cselect_b32 s17, s10, s18
	s_lshl_b32 s12, s45, 21
	s_add_u32 s12, s24, s12
	s_addc_u32 s13, s25, 0
	s_add_u32 s12, s12, s100
	s_addc_u32 s13, s13, 0
	s_and_b64 s[22:23], s[0:1], exec
	s_cselect_b32 s36, s13, s21
	s_cselect_b32 s37, s12, s20
	s_add_u32 s18, s18, 0x100080
	s_addc_u32 s19, s19, 0
	s_add_u32 s46, s20, 0x100
	v_mov_b32_e32 v2, 0
	s_addc_u32 s47, s21, 0
	s_mov_b32 s48, -2
	v_mov_b32_e32 v3, v2
	v_mov_b32_e32 v4, v2
	v_mov_b32_e32 v5, v2
	v_mov_b32_e32 v6, v2
	v_mov_b32_e32 v7, v2
	v_mov_b32_e32 v8, v2
	v_mov_b32_e32 v9, v2
	v_mov_b32_e32 v18, v2
	v_mov_b32_e32 v19, v2
	v_mov_b32_e32 v20, v2
	v_mov_b32_e32 v21, v2
	v_mov_b32_e32 v22, v2
	v_mov_b32_e32 v23, v2
	v_mov_b32_e32 v24, v2
	v_mov_b32_e32 v25, v2
	v_mov_b32_e32 v34, v2
	v_mov_b32_e32 v35, v2
	v_mov_b32_e32 v36, v2
	v_mov_b32_e32 v37, v2
	v_mov_b32_e32 v38, v2
	v_mov_b32_e32 v39, v2
	v_mov_b32_e32 v40, v2
	v_mov_b32_e32 v41, v2
	v_mov_b32_e32 v50, v2
	v_mov_b32_e32 v51, v2
	v_mov_b32_e32 v52, v2
	v_mov_b32_e32 v53, v2
	v_mov_b32_e32 v54, v2
	v_mov_b32_e32 v55, v2
	v_mov_b32_e32 v56, v2
	v_mov_b32_e32 v57, v2
	v_mov_b32_e32 v10, v2
	v_mov_b32_e32 v11, v2
	v_mov_b32_e32 v12, v2
	v_mov_b32_e32 v13, v2
	v_mov_b32_e32 v14, v2
	v_mov_b32_e32 v15, v2
	v_mov_b32_e32 v16, v2
	v_mov_b32_e32 v17, v2
	v_mov_b32_e32 v26, v2
	v_mov_b32_e32 v27, v2
	v_mov_b32_e32 v28, v2
	v_mov_b32_e32 v29, v2
	v_mov_b32_e32 v30, v2
	v_mov_b32_e32 v31, v2
	v_mov_b32_e32 v32, v2
	v_mov_b32_e32 v33, v2
	v_mov_b32_e32 v42, v2
	v_mov_b32_e32 v43, v2
	v_mov_b32_e32 v44, v2
	v_mov_b32_e32 v45, v2
	v_mov_b32_e32 v46, v2
	v_mov_b32_e32 v47, v2
	v_mov_b32_e32 v48, v2
	v_mov_b32_e32 v49, v2
	v_mov_b32_e32 v58, v2
	v_mov_b32_e32 v59, v2
	v_mov_b32_e32 v60, v2
	v_mov_b32_e32 v61, v2
	v_mov_b32_e32 v62, v2
	v_mov_b32_e32 v63, v2
	v_mov_b32_e32 v64, v2
	v_mov_b32_e32 v65, v2
	v_mov_b32_e32 v66, v2
	v_mov_b32_e32 v67, v2
	v_mov_b32_e32 v68, v2
	v_mov_b32_e32 v69, v2
	v_mov_b32_e32 v70, v2
	v_mov_b32_e32 v71, v2
	v_mov_b32_e32 v72, v2
	v_mov_b32_e32 v73, v2
	v_mov_b32_e32 v82, v2
	v_mov_b32_e32 v83, v2
	v_mov_b32_e32 v84, v2
	v_mov_b32_e32 v85, v2
	v_mov_b32_e32 v86, v2
	v_mov_b32_e32 v87, v2
	v_mov_b32_e32 v88, v2
	v_mov_b32_e32 v89, v2
	s_waitcnt vmcnt(0)
	v_mov_b32_e32 v98, v2
	v_mov_b32_e32 v99, v2
	v_mov_b32_e32 v100, v2
	v_mov_b32_e32 v101, v2
	v_mov_b32_e32 v102, v2
	v_mov_b32_e32 v103, v2
	v_mov_b32_e32 v104, v2
	v_mov_b32_e32 v105, v2
	v_mov_b32_e32 v114, v2
	v_mov_b32_e32 v115, v2
	v_mov_b32_e32 v116, v2
	v_mov_b32_e32 v117, v2
	v_mov_b32_e32 v118, v2
	v_mov_b32_e32 v119, v2
	v_mov_b32_e32 v120, v2
	v_mov_b32_e32 v121, v2
	v_mov_b32_e32 v74, v2
	v_mov_b32_e32 v75, v2
	v_mov_b32_e32 v76, v2
	v_mov_b32_e32 v77, v2
	v_mov_b32_e32 v78, v2
	v_mov_b32_e32 v79, v2
	v_mov_b32_e32 v80, v2
	v_mov_b32_e32 v81, v2
	v_mov_b32_e32 v90, v2
	v_mov_b32_e32 v91, v2
	v_mov_b32_e32 v92, v2
	v_mov_b32_e32 v93, v2
	v_mov_b32_e32 v94, v2
	v_mov_b32_e32 v95, v2
	v_mov_b32_e32 v96, v2
	v_mov_b32_e32 v97, v2
	v_mov_b32_e32 v106, v2
	v_mov_b32_e32 v107, v2
	v_mov_b32_e32 v108, v2
	v_mov_b32_e32 v109, v2
	v_mov_b32_e32 v110, v2
	v_mov_b32_e32 v111, v2
	v_mov_b32_e32 v112, v2
	v_mov_b32_e32 v113, v2
	v_mov_b32_e32 v122, v2
	v_mov_b32_e32 v123, v2
	v_mov_b32_e32 v124, v2
	v_mov_b32_e32 v125, v2
	v_mov_b32_e32 v126, v2
	v_mov_b32_e32 v127, v2
	v_mov_b32_e32 v128, v2
	v_mov_b32_e32 v129, v2
.LBB0_1140:
	s_add_u32 s20, s18, 0xfff00080
	s_addc_u32 s21, s19, -1
	s_add_i32 s49, 0, 0x10000
	s_cmp_eq_u32 s48, 60
	s_cselect_b32 s23, s15, s21
	s_cselect_b32 s22, s17, s20
	s_cselect_b32 s21, s36, s47
	s_cselect_b32 s20, s37, s46
	s_cmp_eq_u32 s48, s101
	s_cbranch_scc0 .Lrot_f_top
	s_sub_u32 s22, s22, 0x2000
	s_subb_u32 s23, s23, 0
	s_sub_u32 s20, s20, 0x2000
	s_subb_u32 s21, s21, 0
	s_sub_u32 s46, s46, 0x2000
	s_subb_u32 s47, s47, 0
.Lrot_f_top:
	s_add_i32 s52, 0, 0x14000
	v_add_u32_e32 v142, s49, v184
	v_add_u32_e32 v158, s52, v184
	ds_read_b128 v[130:133], v142
	ds_read_b128 v[134:137], v142 offset:1024
	ds_read_b128 v[138:141], v142 offset:2048
	ds_read_b128 v[142:145], v142 offset:3072
	ds_read_b128 v[146:149], v158
	ds_read_b128 v[150:153], v158 offset:1024
	ds_read_b128 v[154:157], v158 offset:2048
	ds_read_b128 v[158:161], v158 offset:3072
	v_lshl_add_u64 v[182:183], s[18:19], 0, v[168:169]
	s_add_i32 m0, s27, 0xc000
	ds_read_b128 v[178:181], v185
	ds_read_b128 v[186:189], v185 offset:1024
	ds_read_b128 v[190:193], v185 offset:2048
	ds_read_b128 v[194:197], v185 offset:3072
	ds_read_b128 v[198:201], v185 offset:4096
	ds_read_b128 v[202:205], v185 offset:5120
	ds_read_b128 v[206:209], v185 offset:6144
	ds_read_b128 v[210:213], v185 offset:7168
	global_load_lds_dwordx4 v[182:183], off
	v_lshl_add_u64 v[182:183], s[18:19], 0, v[170:171]
	s_add_i32 m0, s27, 0xe000
	s_nop 0
	global_load_lds_dwordx4 v[182:183], off
	s_waitcnt vmcnt(8)
	s_waitcnt lgkmcnt(0)
	s_barrier
; #define WAIT_V(n) asm volatile("s_waitcnt vmcnt(" #n ")" ::: "memory")
; #define WAIT_L(n) asm volatile("s_waitcnt lgkmcnt(" #n ")" ::: "memory")
; #define BAR __builtin_amdgcn_s_barrier()
; #define SCHED __builtin_amdgcn_sched_barrier(0)
;     ...
;       WAIT_V(8); WAIT_L(0); BAR; MMA(0, 0, At, B0); MMA(0, 1, At, B1); BAR; SCHED;
;       LDA(At, 0, 1); STAGE(SBo(0, 0), b2, voffB); STAGE(SBo(0, 1), b2 + hstep, voffB); STAGE(SAo(0, 0), a2, voff);
;       WAIT_V(8); WAIT_L(0); BAR; MMA(1, 0, At, B0); MMA(1, 1, At, B1); BAR; SCHED;
	s_setprio 1
	s_waitcnt lgkmcnt(0)
	v_mfma_f32_16x16x32_bf16 v[126:129], v[130:133], v[178:181], v[126:129]
	v_mfma_f32_16x16x32_bf16 v[122:125], v[138:141], v[178:181], v[122:125]
	v_mfma_f32_16x16x32_bf16 v[110:113], v[130:133], v[190:193], v[110:113]
	v_mfma_f32_16x16x32_bf16 v[106:109], v[138:141], v[190:193], v[106:109]
	v_mfma_f32_16x16x32_bf16 v[94:97], v[130:133], v[198:201], v[94:97]
	v_mfma_f32_16x16x32_bf16 v[90:93], v[138:141], v[198:201], v[90:93]
	v_mfma_f32_16x16x32_bf16 v[78:81], v[130:133], v[206:209], v[78:81]
	v_mfma_f32_16x16x32_bf16 v[74:77], v[138:141], v[206:209], v[74:77]
	v_mfma_f32_16x16x32_bf16 v[126:129], v[134:137], v[186:189], v[126:129]
	v_mfma_f32_16x16x32_bf16 v[122:125], v[142:145], v[186:189], v[122:125]
	v_mfma_f32_16x16x32_bf16 v[110:113], v[134:137], v[194:197], v[110:113]
	v_mfma_f32_16x16x32_bf16 v[106:109], v[142:145], v[194:197], v[106:109]
	v_mfma_f32_16x16x32_bf16 v[94:97], v[134:137], v[202:205], v[94:97]
	v_mfma_f32_16x16x32_bf16 v[90:93], v[142:145], v[202:205], v[90:93]
	v_mfma_f32_16x16x32_bf16 v[78:81], v[134:137], v[210:213], v[78:81]
	v_mfma_f32_16x16x32_bf16 v[74:77], v[142:145], v[210:213], v[74:77]
	s_setprio 0
	s_setprio 1
	v_mfma_f32_16x16x32_bf16 v[118:121], v[146:149], v[178:181], v[118:121]
	v_mfma_f32_16x16x32_bf16 v[114:117], v[154:157], v[178:181], v[114:117]
	v_mfma_f32_16x16x32_bf16 v[102:105], v[146:149], v[190:193], v[102:105]
	v_mfma_f32_16x16x32_bf16 v[98:101], v[154:157], v[190:193], v[98:101]
	v_mfma_f32_16x16x32_bf16 v[86:89], v[146:149], v[198:201], v[86:89]
	v_mfma_f32_16x16x32_bf16 v[82:85], v[154:157], v[198:201], v[82:85]
	v_mfma_f32_16x16x32_bf16 v[70:73], v[146:149], v[206:209], v[70:73]
	v_mfma_f32_16x16x32_bf16 v[66:69], v[154:157], v[206:209], v[66:69]
	v_mfma_f32_16x16x32_bf16 v[118:121], v[150:153], v[186:189], v[118:121]
	v_mfma_f32_16x16x32_bf16 v[114:117], v[158:161], v[186:189], v[114:117]
	v_mfma_f32_16x16x32_bf16 v[102:105], v[150:153], v[194:197], v[102:105]
	v_mfma_f32_16x16x32_bf16 v[98:101], v[158:161], v[194:197], v[98:101]
	v_mfma_f32_16x16x32_bf16 v[86:89], v[150:153], v[202:205], v[86:89]
	v_mfma_f32_16x16x32_bf16 v[82:85], v[158:161], v[202:205], v[82:85]
	v_mfma_f32_16x16x32_bf16 v[70:73], v[150:153], v[210:213], v[70:73]
	v_mfma_f32_16x16x32_bf16 v[66:69], v[158:161], v[210:213], v[66:69]
	s_setprio 0
	s_barrier
	s_add_i32 s49, s49, s26
	v_lshl_add_u64 v[182:183], s[20:21], 0, v[0:1]
	s_mov_b32 m0, s49
	ds_read_b128 v[178:181], v185 offset:16384
	ds_read_b128 v[186:189], v185 offset:17408
	ds_read_b128 v[190:193], v185 offset:18432
	ds_read_b128 v[194:197], v185 offset:19456
	ds_read_b128 v[198:201], v185 offset:20480
	ds_read_b128 v[202:205], v185 offset:21504
	ds_read_b128 v[206:209], v185 offset:22528
	ds_read_b128 v[210:213], v185 offset:23552
	global_load_lds_dwordx4 v[182:183], off
	s_add_i32 m0, s49, 0x2000
	s_add_u32 s50, s20, 0x100000
	v_lshl_add_u64 v[214:215], s[20:21], 0, v[166:167]
	s_addc_u32 s51, s21, 0
	s_add_i32 s49, s52, s26
	global_load_lds_dwordx4 v[214:215], off
	v_lshl_add_u64 v[216:217], s[50:51], 0, v[0:1]
	s_mov_b32 m0, s49
	v_lshl_add_u64 v[218:219], s[22:23], 0, v[164:165]
	global_load_lds_dwordx4 v[216:217], off
	v_lshl_add_u64 v[216:217], s[50:51], 0, v[166:167]
	s_add_i32 m0, s49, 0x2000
	s_nop 0
	global_load_lds_dwordx4 v[216:217], off
	v_lshl_add_u64 v[216:217], s[22:23], 0, v[162:163]
	s_mov_b32 m0, s27
	s_nop 0
	global_load_lds_dwordx4 v[216:217], off
	s_mov_b32 m0, s29
	s_nop 0
	global_load_lds_dwordx4 v[218:219], off
	s_waitcnt vmcnt(8)
	s_waitcnt lgkmcnt(0)
	s_barrier
	s_setprio 1
	s_waitcnt lgkmcnt(0)
	v_mfma_f32_16x16x32_bf16 v[62:65], v[130:133], v[178:181], v[62:65]
	v_mfma_f32_16x16x32_bf16 v[58:61], v[138:141], v[178:181], v[58:61]
	v_mfma_f32_16x16x32_bf16 v[46:49], v[130:133], v[190:193], v[46:49]
	v_mfma_f32_16x16x32_bf16 v[42:45], v[138:141], v[190:193], v[42:45]
	v_mfma_f32_16x16x32_bf16 v[30:33], v[130:133], v[198:201], v[30:33]
	v_mfma_f32_16x16x32_bf16 v[26:29], v[138:141], v[198:201], v[26:29]
	v_mfma_f32_16x16x32_bf16 v[14:17], v[130:133], v[206:209], v[14:17]
	v_mfma_f32_16x16x32_bf16 v[10:13], v[138:141], v[206:209], v[10:13]
	v_mfma_f32_16x16x32_bf16 v[62:65], v[134:137], v[186:189], v[62:65]
	v_mfma_f32_16x16x32_bf16 v[58:61], v[142:145], v[186:189], v[58:61]
	v_mfma_f32_16x16x32_bf16 v[46:49], v[134:137], v[194:197], v[46:49]
	v_mfma_f32_16x16x32_bf16 v[42:45], v[142:145], v[194:197], v[42:45]
	v_mfma_f32_16x16x32_bf16 v[30:33], v[134:137], v[202:205], v[30:33]
	v_mfma_f32_16x16x32_bf16 v[26:29], v[142:145], v[202:205], v[26:29]
	v_mfma_f32_16x16x32_bf16 v[14:17], v[134:137], v[210:213], v[14:17]
	v_mfma_f32_16x16x32_bf16 v[10:13], v[142:145], v[210:213], v[10:13]
	s_setprio 0
	s_setprio 1
	v_mfma_f32_16x16x32_bf16 v[54:57], v[146:149], v[178:181], v[54:57]
	v_mfma_f32_16x16x32_bf16 v[50:53], v[154:157], v[178:181], v[50:53]
	v_mfma_f32_16x16x32_bf16 v[38:41], v[146:149], v[190:193], v[38:41]
	v_mfma_f32_16x16x32_bf16 v[34:37], v[154:157], v[190:193], v[34:37]
	v_mfma_f32_16x16x32_bf16 v[22:25], v[146:149], v[198:201], v[22:25]
	v_mfma_f32_16x16x32_bf16 v[18:21], v[154:157], v[198:201], v[18:21]
	v_mfma_f32_16x16x32_bf16 v[6:9], v[146:149], v[206:209], v[6:9]
	v_mfma_f32_16x16x32_bf16 v[2:5], v[154:157], v[206:209], v[2:5]
	v_mfma_f32_16x16x32_bf16 v[54:57], v[150:153], v[186:189], v[54:57]
	v_mfma_f32_16x16x32_bf16 v[50:53], v[158:161], v[186:189], v[50:53]
	v_mfma_f32_16x16x32_bf16 v[38:41], v[150:153], v[194:197], v[38:41]
	v_mfma_f32_16x16x32_bf16 v[34:37], v[158:161], v[194:197], v[34:37]
	v_mfma_f32_16x16x32_bf16 v[22:25], v[150:153], v[202:205], v[22:25]
	v_mfma_f32_16x16x32_bf16 v[18:21], v[158:161], v[202:205], v[18:21]
	v_mfma_f32_16x16x32_bf16 v[6:9], v[150:153], v[210:213], v[6:9]
	v_mfma_f32_16x16x32_bf16 v[2:5], v[158:161], v[210:213], v[2:5]
	s_setprio 0
	s_barrier
; #define WAIT_V(n) asm volatile("s_waitcnt vmcnt(" #n ")" ::: "memory")
; #define WAIT_L(n) asm volatile("s_waitcnt lgkmcnt(" #n ")" ::: "memory")
; #define BAR __builtin_amdgcn_s_barrier()
; #define SCHED __builtin_amdgcn_sched_barrier(0)
;     ...
;       LDB(B0, 1, 0); LDB(B1, 1, 1); SCHED; LDA(At, 1, 0); STAGE(SAo(0, 1), a2 + hstep, voff);
;       WAIT_V(8); WAIT_L(0); BAR; MMA(0, 0, At, B0); MMA(0, 1, At, B1); BAR; SCHED;
	s_add_i32 s49, 0, 0x18000
	s_add_i32 s50, 0, 0x1c000
	v_add_u32_e32 v142, s49, v184
	v_add_u32_e32 v158, s50, v184
	ds_read_b128 v[130:133], v142
	ds_read_b128 v[134:137], v142 offset:1024
	ds_read_b128 v[138:141], v142 offset:2048
	ds_read_b128 v[142:145], v142 offset:3072
	ds_read_b128 v[146:149], v158
	ds_read_b128 v[150:153], v158 offset:1024
	ds_read_b128 v[154:157], v158 offset:2048
	ds_read_b128 v[158:161], v158 offset:3072
	s_add_u32 s22, s22, 0x100000
	s_addc_u32 s23, s23, 0
	s_mov_b32 m0, s30
	v_lshl_add_u64 v[220:221], s[22:23], 0, v[162:163]
	ds_read_b128 v[178:181], v185 offset:32768
	ds_read_b128 v[186:189], v185 offset:33792
	ds_read_b128 v[190:193], v185 offset:34816
	ds_read_b128 v[194:197], v185 offset:35840
	ds_read_b128 v[198:201], v185 offset:36864
	ds_read_b128 v[202:205], v185 offset:37888
	ds_read_b128 v[206:209], v185 offset:38912
	ds_read_b128 v[210:213], v185 offset:39936
	global_load_lds_dwordx4 v[220:221], off
	v_lshl_add_u64 v[220:221], s[22:23], 0, v[164:165]
	s_mov_b32 m0, s31
	s_nop 0
	global_load_lds_dwordx4 v[220:221], off
	s_waitcnt vmcnt(8)
	s_waitcnt lgkmcnt(0)
	s_barrier
	s_setprio 1
	s_waitcnt lgkmcnt(0)
	v_mfma_f32_16x16x32_bf16 v[126:129], v[130:133], v[178:181], v[126:129]
	v_mfma_f32_16x16x32_bf16 v[122:125], v[138:141], v[178:181], v[122:125]
	v_mfma_f32_16x16x32_bf16 v[110:113], v[130:133], v[190:193], v[110:113]
	v_mfma_f32_16x16x32_bf16 v[106:109], v[138:141], v[190:193], v[106:109]
	v_mfma_f32_16x16x32_bf16 v[94:97], v[130:133], v[198:201], v[94:97]
	v_mfma_f32_16x16x32_bf16 v[90:93], v[138:141], v[198:201], v[90:93]
	v_mfma_f32_16x16x32_bf16 v[78:81], v[130:133], v[206:209], v[78:81]
	v_mfma_f32_16x16x32_bf16 v[74:77], v[138:141], v[206:209], v[74:77]
	v_mfma_f32_16x16x32_bf16 v[126:129], v[134:137], v[186:189], v[126:129]
	v_mfma_f32_16x16x32_bf16 v[122:125], v[142:145], v[186:189], v[122:125]
	v_mfma_f32_16x16x32_bf16 v[110:113], v[134:137], v[194:197], v[110:113]
	v_mfma_f32_16x16x32_bf16 v[106:109], v[142:145], v[194:197], v[106:109]
	v_mfma_f32_16x16x32_bf16 v[94:97], v[134:137], v[202:205], v[94:97]
	v_mfma_f32_16x16x32_bf16 v[90:93], v[142:145], v[202:205], v[90:93]
	v_mfma_f32_16x16x32_bf16 v[78:81], v[134:137], v[210:213], v[78:81]
	v_mfma_f32_16x16x32_bf16 v[74:77], v[142:145], v[210:213], v[74:77]
	s_setprio 0
	s_setprio 1
	v_mfma_f32_16x16x32_bf16 v[118:121], v[146:149], v[178:181], v[118:121]
	v_mfma_f32_16x16x32_bf16 v[114:117], v[154:157], v[178:181], v[114:117]
	v_mfma_f32_16x16x32_bf16 v[102:105], v[146:149], v[190:193], v[102:105]
	v_mfma_f32_16x16x32_bf16 v[98:101], v[154:157], v[190:193], v[98:101]
	v_mfma_f32_16x16x32_bf16 v[86:89], v[146:149], v[198:201], v[86:89]
	v_mfma_f32_16x16x32_bf16 v[82:85], v[154:157], v[198:201], v[82:85]
	v_mfma_f32_16x16x32_bf16 v[70:73], v[146:149], v[206:209], v[70:73]
	v_mfma_f32_16x16x32_bf16 v[66:69], v[154:157], v[206:209], v[66:69]
	v_mfma_f32_16x16x32_bf16 v[118:121], v[150:153], v[186:189], v[118:121]
	v_mfma_f32_16x16x32_bf16 v[114:117], v[158:161], v[186:189], v[114:117]
	v_mfma_f32_16x16x32_bf16 v[102:105], v[150:153], v[194:197], v[102:105]
	v_mfma_f32_16x16x32_bf16 v[98:101], v[158:161], v[194:197], v[98:101]
	v_mfma_f32_16x16x32_bf16 v[86:89], v[150:153], v[202:205], v[86:89]
	v_mfma_f32_16x16x32_bf16 v[82:85], v[158:161], v[202:205], v[82:85]
	v_mfma_f32_16x16x32_bf16 v[70:73], v[150:153], v[210:213], v[70:73]
	v_mfma_f32_16x16x32_bf16 v[66:69], v[158:161], v[210:213], v[66:69]
	s_setprio 0
	s_barrier
; #define WAIT_V(n) asm volatile("s_waitcnt vmcnt(" #n ")" ::: "memory")
; #define WAIT_L(n) asm volatile("s_waitcnt lgkmcnt(" #n ")" ::: "memory")
; #define BAR __builtin_amdgcn_s_barrier()
; #define SCHED __builtin_amdgcn_sched_barrier(0)
;     ...
;       LDA(At, 1, 1); STAGE(SBo(1, 0), b3, voffB); STAGE(SBo(1, 1), b3 + hstep, voffB); STAGE(SAo(1, 0), a3, voff);
;       WAIT_V(8); WAIT_L(0); BAR; MMA(1, 0, At, B0); MMA(1, 1, At, B1); BAR; SCHED;
;     }
	s_add_i32 s22, s49, s26
	v_lshl_add_u64 v[182:183], v[182:183], 0, s[34:35]
	s_mov_b32 m0, s22
	ds_read_b128 v[178:181], v185 offset:49152
	ds_read_b128 v[186:189], v185 offset:50176
	ds_read_b128 v[190:193], v185 offset:51200
	ds_read_b128 v[194:197], v185 offset:52224
	ds_read_b128 v[198:201], v185 offset:53248
	ds_read_b128 v[202:205], v185 offset:54272
	ds_read_b128 v[206:209], v185 offset:55296
	ds_read_b128 v[210:213], v185 offset:56320
	global_load_lds_dwordx4 v[182:183], off
	s_add_i32 m0, s22, 0x2000
	s_add_u32 s20, s20, 0x100080
	v_lshl_add_u64 v[182:183], v[214:215], 0, s[34:35]
	s_addc_u32 s21, s21, 0
	s_add_i32 s22, s50, s26
	global_load_lds_dwordx4 v[182:183], off
	v_lshl_add_u64 v[182:183], s[20:21], 0, v[0:1]
	s_mov_b32 m0, s22
	s_nop 0
	global_load_lds_dwordx4 v[182:183], off
	v_lshl_add_u64 v[182:183], s[20:21], 0, v[166:167]
	s_add_i32 m0, s22, 0x2000
	s_nop 0
	global_load_lds_dwordx4 v[182:183], off
	v_lshl_add_u64 v[182:183], v[216:217], 0, s[34:35]
	s_mov_b32 m0, s39
	s_nop 0
	global_load_lds_dwordx4 v[182:183], off
	v_lshl_add_u64 v[182:183], v[218:219], 0, s[34:35]
	s_mov_b32 m0, s42
	s_nop 0
	global_load_lds_dwordx4 v[182:183], off
	s_waitcnt vmcnt(8)
	s_waitcnt lgkmcnt(0)
	s_barrier
	s_setprio 1
	s_waitcnt lgkmcnt(0)
	v_mfma_f32_16x16x32_bf16 v[62:65], v[130:133], v[178:181], v[62:65]
	v_mfma_f32_16x16x32_bf16 v[58:61], v[138:141], v[178:181], v[58:61]
	v_mfma_f32_16x16x32_bf16 v[46:49], v[130:133], v[190:193], v[46:49]
	v_mfma_f32_16x16x32_bf16 v[42:45], v[138:141], v[190:193], v[42:45]
	v_mfma_f32_16x16x32_bf16 v[30:33], v[130:133], v[198:201], v[30:33]
	v_mfma_f32_16x16x32_bf16 v[26:29], v[138:141], v[198:201], v[26:29]
	v_mfma_f32_16x16x32_bf16 v[14:17], v[130:133], v[206:209], v[14:17]
	v_mfma_f32_16x16x32_bf16 v[10:13], v[138:141], v[206:209], v[10:13]
	v_mfma_f32_16x16x32_bf16 v[62:65], v[134:137], v[186:189], v[62:65]
	v_mfma_f32_16x16x32_bf16 v[58:61], v[142:145], v[186:189], v[58:61]
	v_mfma_f32_16x16x32_bf16 v[46:49], v[134:137], v[194:197], v[46:49]
	v_mfma_f32_16x16x32_bf16 v[42:45], v[142:145], v[194:197], v[42:45]
	v_mfma_f32_16x16x32_bf16 v[30:33], v[134:137], v[202:205], v[30:33]
	v_mfma_f32_16x16x32_bf16 v[26:29], v[142:145], v[202:205], v[26:29]
	v_mfma_f32_16x16x32_bf16 v[14:17], v[134:137], v[210:213], v[14:17]
	v_mfma_f32_16x16x32_bf16 v[10:13], v[142:145], v[210:213], v[10:13]
	s_setprio 0
	s_setprio 1
	v_mfma_f32_16x16x32_bf16 v[54:57], v[146:149], v[178:181], v[54:57]
	v_mfma_f32_16x16x32_bf16 v[50:53], v[154:157], v[178:181], v[50:53]
	v_mfma_f32_16x16x32_bf16 v[38:41], v[146:149], v[190:193], v[38:41]
	v_mfma_f32_16x16x32_bf16 v[34:37], v[154:157], v[190:193], v[34:37]
	v_mfma_f32_16x16x32_bf16 v[22:25], v[146:149], v[198:201], v[22:25]
	v_mfma_f32_16x16x32_bf16 v[18:21], v[154:157], v[198:201], v[18:21]
	v_mfma_f32_16x16x32_bf16 v[6:9], v[146:149], v[206:209], v[6:9]
	v_mfma_f32_16x16x32_bf16 v[2:5], v[154:157], v[206:209], v[2:5]
	v_mfma_f32_16x16x32_bf16 v[54:57], v[150:153], v[186:189], v[54:57]
	v_mfma_f32_16x16x32_bf16 v[50:53], v[158:161], v[186:189], v[50:53]
	v_mfma_f32_16x16x32_bf16 v[38:41], v[150:153], v[194:197], v[38:41]
	v_mfma_f32_16x16x32_bf16 v[34:37], v[158:161], v[194:197], v[34:37]
	v_mfma_f32_16x16x32_bf16 v[22:25], v[150:153], v[202:205], v[22:25]
	v_mfma_f32_16x16x32_bf16 v[18:21], v[158:161], v[202:205], v[18:21]
	v_mfma_f32_16x16x32_bf16 v[6:9], v[150:153], v[210:213], v[6:9]
	v_mfma_f32_16x16x32_bf16 v[2:5], v[158:161], v[210:213], v[2:5]
	s_setprio 0
	s_barrier
	s_cmp_eq_u32 s48, s101
	s_cbranch_scc0 .Lrot_f_tail
	s_sub_u32 s18, s18, 0x2000
	s_subb_u32 s19, s19, 0
.Lrot_f_tail:
	s_add_i32 s48, s48, 2
	s_add_u32 s18, s18, 0x100
	s_addc_u32 s19, s19, 0
	s_add_u32 s46, s46, 0x100
	s_addc_u32 s47, s47, 0
	s_cmp_gt_u32 s48, 61
	s_cbranch_scc0 .LBB0_1140
	s_and_b64 vcc, exec, s[8:9]
	s_cbranch_vccz .LBB0_1143
	s_barrier
